# v16 + batched LDS reads in the S5 pass-B scan loop (4 steps per LDS round trip)
# speedup vs baseline: 1.0128x; 1.0007x over previous
; DEVI bf16_t f2bf(float f) { return (bf16_t)(pk_bf16(f, 0.f) & 0xffffu); }
; DEVI float bf2f(bf16_t v) { return __uint_as_float((unsigned)v << 16); }
; DEVI void s5_pass_b(const Params& p, int l, int witem, unsigned char* wlraw) {
;     ...
; #pragma unroll 4
;         for (int tt = 0; tt < 32; ++tt) {
;             const float xr = bf2f(Hs[tt * 136 + lane]), xi = bf2f(Hs[tt * 136 + 64 + lane]);
;             const float nr = a4.x * hr - a4.y * hi + xr, ni = a4.x * hi + a4.y * hr + xi;
;             hr = nr; hi = ni;
;             Hs[tt * 136 + lane] = f2bf(hr);
;             Hs[tt * 136 + 64 + lane] = f2bf(hi);
;         }
.LBB0_717:
	v_add_u32_e32 v68, s26, v66
	ds_read_u16 v54, v68
	ds_read_u16 v55, v68 offset:128
	ds_read_u16 v92, v68 offset:272
	ds_read_u16 v93, v68 offset:400
	ds_read_u16 v94, v68 offset:544
	ds_read_u16 v95, v68 offset:672
	ds_read_u16 v96, v68 offset:816
	ds_read_u16 v97, v68 offset:944
	v_pk_mul_f32 v[52:53], v[62:63], v[72:73] op_sel:[0,1]
	s_addk_i32 s26, 0x440
	v_pk_fma_f32 v[56:57], v[2:3], v[72:73], v[52:53] neg_lo:[0,0,1] neg_hi:[0,0,1]
	v_pk_fma_f32 v[52:53], v[2:3], v[72:73], v[52:53] op_sel_hi:[1,0,1]
	s_waitcnt lgkmcnt(6)
	v_lshlrev_b32_e32 v55, 16, v55
	v_lshlrev_b32_e32 v54, 16, v54
	v_mov_b32_e32 v57, v53
	v_pk_add_f32 v[52:53], v[56:57], v[54:55]
	s_cmpk_eq_i32 s26, 0x3200
	v_cvt_pk_bf16_f32 v54, v52, s0
	ds_write_b16 v68, v54
	v_cvt_pk_bf16_f32 v54, v53, s0
	ds_write_b16 v68, v54 offset:128
	v_pk_mul_f32 v[54:55], v[62:63], v[52:53] op_sel:[0,1]
	s_waitcnt lgkmcnt(6)
	v_lshlrev_b32_e32 v56, 16, v92
	v_pk_fma_f32 v[58:59], v[2:3], v[52:53], v[54:55] neg_lo:[0,0,1] neg_hi:[0,0,1]
	v_pk_fma_f32 v[52:53], v[2:3], v[52:53], v[54:55] op_sel_hi:[1,0,1]
	s_waitcnt lgkmcnt(6)
	v_lshlrev_b32_e32 v57, 16, v93
	v_mov_b32_e32 v59, v53
	v_pk_add_f32 v[52:53], v[58:59], v[56:57]
	s_nop 0
	v_cvt_pk_bf16_f32 v54, v52, s0
	ds_write_b16 v68, v54 offset:272
	v_cvt_pk_bf16_f32 v54, v53, s0
	ds_write_b16 v68, v54 offset:400
	v_pk_mul_f32 v[54:55], v[62:63], v[52:53] op_sel:[0,1]
	s_waitcnt lgkmcnt(6)
	v_lshlrev_b32_e32 v56, 16, v94
	v_pk_fma_f32 v[58:59], v[2:3], v[52:53], v[54:55] neg_lo:[0,0,1] neg_hi:[0,0,1]
	v_pk_fma_f32 v[52:53], v[2:3], v[52:53], v[54:55] op_sel_hi:[1,0,1]
	s_waitcnt lgkmcnt(6)
	v_lshlrev_b32_e32 v57, 16, v95
	v_mov_b32_e32 v59, v53
	v_pk_add_f32 v[52:53], v[58:59], v[56:57]
	s_nop 0
	v_cvt_pk_bf16_f32 v54, v52, s0
	ds_write_b16 v68, v54 offset:544
	v_cvt_pk_bf16_f32 v54, v53, s0
	ds_write_b16 v68, v54 offset:672
	v_pk_mul_f32 v[54:55], v[62:63], v[52:53] op_sel:[0,1]
	s_waitcnt lgkmcnt(6)
	v_lshlrev_b32_e32 v56, 16, v96
	v_pk_fma_f32 v[58:59], v[2:3], v[52:53], v[54:55] neg_lo:[0,0,1] neg_hi:[0,0,1]
	v_pk_fma_f32 v[52:53], v[2:3], v[52:53], v[54:55] op_sel_hi:[1,0,1]
	s_waitcnt lgkmcnt(6)
	v_lshlrev_b32_e32 v57, 16, v97
	v_mov_b32_e32 v59, v53
	v_pk_add_f32 v[72:73], v[58:59], v[56:57]
	s_nop 0
	v_cvt_pk_bf16_f32 v52, v72, s0
	ds_write_b16 v68, v52 offset:816
	v_cvt_pk_bf16_f32 v52, v73, s0
	ds_write_b16 v68, v52 offset:944
	s_cbranch_scc0 .LBB0_717
; DEVI int wave_() { return __builtin_amdgcn_readfirstlane(tid_() >> 6); }
; DEVI bf16_t f2bf(float f) { return (bf16_t)(pk_bf16(f, 0.f) & 0xffffu); }
; DEVI f32x4 mfma16(bf16x8 a, bf16x8 b, f32x4 c) { return __builtin_amdgcn_mfma_f32_16x16x32_bf16(a, b, c, 0, 0, 0); }
; DEVI void s5_pass_b(const Params& p, int l, int witem, unsigned char* wlraw) {
;     ...
;         f32x4 y[2];
; #pragma unroll
;         for (int mt = 0; mt < 2; ++mt) {
;             y[mt] = (f32x4){0.f, 0.f, 0.f, 0.f};
; #pragma unroll
;             for (int ks = 0; ks < 4; ++ks) {
;                 const bf16x8 hf = *(const bf16x8*)(Hs + (mt * 16 + l16) * 136 + ks * 32 + quad * 8);
;                 y[mt] = mfma16(hf, cf[ks], y[mt]);
;             }
;         }
; #pragma unroll
;         for (int mt = 0; mt < 2; ++mt)
; #pragma unroll
;             for (int r = 0; r < 4; ++r) {
;                 const int t = half * 32 + mt * 16 + quad * 4 + r;
;                 const float yy = y[mt][r] + dsk * us[t * 16 + l16];
;                 yg[(size_t)(tok0 + t) * 256 + G * 16 + l16] = f2bf(gelu_tanh(yy));
;             }
; DEVI void phase_m3(const Params& p, int l, unsigned char* smem) {
;     ...
;     for (int i = bid; i < 1024; i += G) {
;         const int wv = wave_();
;         int wi = i * 4 + wv;
;         if (i >= 512) { const int k = (wi >> 4) & 127; wi = (wi & ~(127 << 4)) | ((127 - k) << 4); }
;         __syncthreads();
;         s5_pass_b(p, l, wi, smem + wv * 16384);
	ds_read_b128 v[52:55], v67 offset:4096
	ds_read_b128 v[56:59], v67 offset:4160
	s_mov_b64 s[26:27], 0
	s_and_b64 vcc, exec, s[24:25]
	s_waitcnt lgkmcnt(1)
	v_mfma_f32_16x16x32_bf16 v[52:55], v[52:55], v[36:39], 0
	ds_read_b128 v[68:71], v67 offset:8512
	s_waitcnt lgkmcnt(1)
	v_mfma_f32_16x16x32_bf16 v[52:55], v[56:59], v[40:43], v[52:55]
	ds_read_b128 v[56:59], v67 offset:4224
	s_waitcnt lgkmcnt(0)
	v_mfma_f32_16x16x32_bf16 v[52:55], v[56:59], v[44:47], v[52:55]
	ds_read_b128 v[56:59], v67 offset:4288
	s_waitcnt lgkmcnt(0)
	v_mfma_f32_16x16x32_bf16 v[56:59], v[56:59], v[48:51], v[52:55]
	s_nop 4
	ds_read_b128 v[52:55], v67 offset:8448
	s_waitcnt lgkmcnt(0)
	v_mfma_f32_16x16x32_bf16 v[52:55], v[52:55], v[36:39], 0
	v_mfma_f32_16x16x32_bf16 v[52:55], v[68:71], v[40:43], v[52:55]
	ds_read_b128 v[68:71], v67 offset:8576
	s_waitcnt lgkmcnt(0)
	v_mfma_f32_16x16x32_bf16 v[52:55], v[68:71], v[44:47], v[52:55]
	ds_read_b128 v[68:71], v67 offset:8640
	s_waitcnt lgkmcnt(0)
	v_mfma_f32_16x16x32_bf16 v[52:55], v[68:71], v[48:51], v[52:55]
	v_or_b32_e32 v68, s22, v65
	v_lshl_add_u32 v69, v68, 6, v0
	ds_read_b32 v69, v69
	v_or_b32_e32 v70, s40, v68
	v_ashrrev_i32_e32 v71, 31, v70
	v_lshlrev_b64 v[70:71], 9, v[70:71]
	v_lshl_add_u64 v[70:71], v[60:61], 0, v[70:71]
	s_waitcnt lgkmcnt(0)
	v_fma_f32 v56, v64, v69, v56
	v_mul_f32_e32 v69, 0x3d372713, v56
	v_mul_f32_e32 v69, v56, v69
	v_fma_f32 v69, v56, v69, v56
	v_mul_f32_e32 v69, 0x3f4c422a, v69
	v_mul_f32_e32 v69, 0x4038aa3b, v69
	v_exp_f32_e32 v69, v69
	v_mul_f32_e32 v56, 0.5, v56
	s_mov_b32 s22, 32
	v_add_f32_e32 v69, 1.0, v69
	v_rcp_f32_e32 v69, v69
	s_nop 0
	v_fma_f32 v69, v69, -2.0, 1.0
	v_add_f32_e32 v69, 1.0, v69
	v_mul_f32_e32 v56, v56, v69
	v_cvt_pk_bf16_f32 v56, v56, s0
	global_store_short v[70:71], v56, off
	v_or_b32_e32 v56, 1, v68
	v_lshl_add_u32 v69, v56, 6, v0
	ds_read_b32 v69, v69
	v_or_b32_e32 v56, s40, v56
	s_waitcnt lgkmcnt(0)
	v_fma_f32 v57, v64, v69, v57
	v_mul_f32_e32 v69, 0x3d372713, v57
	v_mul_f32_e32 v69, v57, v69
	v_fma_f32 v69, v57, v69, v57
	v_mul_f32_e32 v69, 0x3f4c422a, v69
	v_mul_f32_e32 v69, 0x4038aa3b, v69
	v_exp_f32_e32 v69, v69
	v_mul_f32_e32 v57, 0.5, v57
	v_add_f32_e32 v69, 1.0, v69
	v_rcp_f32_e32 v69, v69
	s_nop 0
	v_fma_f32 v69, v69, -2.0, 1.0
	v_add_f32_e32 v69, 1.0, v69
	v_mul_f32_e32 v57, v57, v69
	v_cvt_pk_bf16_f32 v69, v57, s0
	v_ashrrev_i32_e32 v57, 31, v56
	v_lshlrev_b64 v[56:57], 9, v[56:57]
	v_lshl_add_u64 v[56:57], v[60:61], 0, v[56:57]
	global_store_short v[56:57], v69, off
	v_or_b32_e32 v56, 2, v68
	v_lshl_add_u32 v57, v56, 6, v0
	ds_read_b32 v57, v57
	v_or_b32_e32 v56, s40, v56
	s_waitcnt lgkmcnt(0)
	v_fma_f32 v57, v64, v57, v58
	v_mul_f32_e32 v58, 0x3d372713, v57
	v_mul_f32_e32 v58, v57, v58
	v_fma_f32 v58, v57, v58, v57
	v_mul_f32_e32 v58, 0x3f4c422a, v58
	v_mul_f32_e32 v58, 0x4038aa3b, v58
	v_exp_f32_e32 v58, v58
	v_mul_f32_e32 v57, 0.5, v57
	v_add_f32_e32 v58, 1.0, v58
	v_rcp_f32_e32 v58, v58
	s_nop 0
	v_fma_f32 v58, v58, -2.0, 1.0
	v_add_f32_e32 v58, 1.0, v58
	v_mul_f32_e32 v57, v57, v58
	v_cvt_pk_bf16_f32 v58, v57, s0
	v_ashrrev_i32_e32 v57, 31, v56
	v_lshlrev_b64 v[56:57], 9, v[56:57]
	v_lshl_add_u64 v[56:57], v[60:61], 0, v[56:57]
	global_store_short v[56:57], v58, off
	v_or_b32_e32 v56, 3, v68
	v_lshl_add_u32 v57, v56, 6, v0
	ds_read_b32 v57, v57
	v_or_b32_e32 v56, s40, v56
	s_waitcnt lgkmcnt(0)
	v_fmac_f32_e32 v59, v64, v57
	v_mul_f32_e32 v57, 0x3d372713, v59
	v_mul_f32_e32 v57, v59, v57
	v_fma_f32 v57, v59, v57, v59
	v_mul_f32_e32 v57, 0x3f4c422a, v57
	v_mul_f32_e32 v57, 0x4038aa3b, v57
	v_exp_f32_e32 v57, v57
	v_mul_f32_e32 v58, 0.5, v59
	v_add_f32_e32 v57, 1.0, v57
	v_rcp_f32_e32 v57, v57
	s_nop 0
	v_fma_f32 v57, v57, -2.0, 1.0
	v_add_f32_e32 v57, 1.0, v57
	v_mul_f32_e32 v57, v58, v57
	v_cvt_pk_bf16_f32 v58, v57, s0
	v_ashrrev_i32_e32 v57, 31, v56
	v_lshlrev_b64 v[56:57], 9, v[56:57]
	v_lshl_add_u64 v[56:57], v[60:61], 0, v[56:57]
	global_store_short v[56:57], v58, off
	v_or_b32_e32 v56, 16, v68
	v_lshl_add_u32 v57, v56, 6, v0
	ds_read_b32 v57, v57
	v_or_b32_e32 v56, s40, v56
	s_waitcnt lgkmcnt(0)
	v_fma_f32 v52, v64, v57, v52
	v_mul_f32_e32 v57, 0x3d372713, v52
	v_mul_f32_e32 v57, v52, v57
	v_fma_f32 v57, v52, v57, v52
	v_mul_f32_e32 v57, 0x3f4c422a, v57
	v_mul_f32_e32 v57, 0x4038aa3b, v57
	v_exp_f32_e32 v57, v57
	v_mul_f32_e32 v52, 0.5, v52
	v_add_f32_e32 v57, 1.0, v57
	v_rcp_f32_e32 v57, v57
	s_nop 0
	v_fma_f32 v57, v57, -2.0, 1.0
	v_add_f32_e32 v57, 1.0, v57
	v_mul_f32_e32 v52, v52, v57
	v_ashrrev_i32_e32 v57, 31, v56
	v_lshlrev_b64 v[56:57], 9, v[56:57]
	v_cvt_pk_bf16_f32 v52, v52, s0
	v_lshl_add_u64 v[56:57], v[60:61], 0, v[56:57]
	global_store_short v[56:57], v52, off
	v_or_b32_e32 v52, 17, v68
	v_lshl_add_u32 v56, v52, 6, v0
	ds_read_b32 v56, v56
	v_or_b32_e32 v52, s40, v52
	s_waitcnt lgkmcnt(0)
	v_fma_f32 v53, v64, v56, v53
	v_mul_f32_e32 v56, 0x3d372713, v53
	v_mul_f32_e32 v56, v53, v56
	v_fma_f32 v56, v53, v56, v53
	v_mul_f32_e32 v56, 0x3f4c422a, v56
	v_mul_f32_e32 v56, 0x4038aa3b, v56
	v_exp_f32_e32 v56, v56
	v_mul_f32_e32 v53, 0.5, v53
	v_add_f32_e32 v56, 1.0, v56
	v_rcp_f32_e32 v56, v56
	s_nop 0
	v_fma_f32 v56, v56, -2.0, 1.0
	v_add_f32_e32 v56, 1.0, v56
	v_mul_f32_e32 v53, v53, v56
	v_cvt_pk_bf16_f32 v56, v53, s0
	v_ashrrev_i32_e32 v53, 31, v52
	v_lshlrev_b64 v[52:53], 9, v[52:53]
	v_lshl_add_u64 v[52:53], v[60:61], 0, v[52:53]
	global_store_short v[52:53], v56, off
	v_or_b32_e32 v52, 18, v68
	v_lshl_add_u32 v53, v52, 6, v0
	ds_read_b32 v53, v53
	v_or_b32_e32 v52, s40, v52
	s_waitcnt lgkmcnt(0)
	v_fma_f32 v53, v64, v53, v54
	v_mul_f32_e32 v54, 0x3d372713, v53
	v_mul_f32_e32 v54, v53, v54
	v_fma_f32 v54, v53, v54, v53
	v_mul_f32_e32 v54, 0x3f4c422a, v54
	v_mul_f32_e32 v54, 0x4038aa3b, v54
	v_exp_f32_e32 v54, v54
	v_mul_f32_e32 v53, 0.5, v53
	v_add_f32_e32 v54, 1.0, v54
	v_rcp_f32_e32 v54, v54
	s_nop 0
	v_fma_f32 v54, v54, -2.0, 1.0
	v_add_f32_e32 v54, 1.0, v54
	v_mul_f32_e32 v53, v53, v54
	v_cvt_pk_bf16_f32 v54, v53, s0
	v_ashrrev_i32_e32 v53, 31, v52
	v_lshlrev_b64 v[52:53], 9, v[52:53]
	v_lshl_add_u64 v[52:53], v[60:61], 0, v[52:53]
	global_store_short v[52:53], v54, off
	v_or_b32_e32 v52, 19, v68
	v_lshl_add_u32 v53, v52, 6, v0
	ds_read_b32 v53, v53
	v_or_b32_e32 v52, s40, v52
	s_waitcnt lgkmcnt(0)
	v_fmac_f32_e32 v55, v64, v53
	v_mul_f32_e32 v53, 0x3d372713, v55
	v_mul_f32_e32 v53, v55, v53
	v_fma_f32 v53, v55, v53, v55
	v_mul_f32_e32 v53, 0x3f4c422a, v53
	v_mul_f32_e32 v53, 0x4038aa3b, v53
	v_exp_f32_e32 v53, v53
	v_mul_f32_e32 v54, 0.5, v55
	v_add_f32_e32 v53, 1.0, v53
	v_rcp_f32_e32 v53, v53
	s_nop 0
	v_fma_f32 v53, v53, -2.0, 1.0
	v_add_f32_e32 v53, 1.0, v53
	v_mul_f32_e32 v53, v54, v53
	v_cvt_pk_bf16_f32 v54, v53, s0
	v_ashrrev_i32_e32 v53, 31, v52
	v_lshlrev_b64 v[52:53], 9, v[52:53]
	v_lshl_add_u64 v[52:53], v[60:61], 0, v[52:53]
	global_store_short v[52:53], v54, off
	s_cbranch_vccz .LBB0_716
	s_add_i32 s38, s38, s53
	s_cmpk_gt_i32 s38, 0x3ff
	s_cbranch_scc0 .LBB0_706
